# prep phase: loop-invariant conv/gain weight loads hoisted out of the per-row loop into persistent VGPRs
# speedup vs baseline: 1.0166x; 1.0166x over previous
; __device__ __forceinline__ int ltid() { int t = threadIdx.x; asm volatile("" : "+v"(t)); return t; }
; __device__ __forceinline__ int lbid() { int t = blockIdx.x; asm volatile("" : "+s"(t)); return t; }
; __device__ __forceinline__ void prep_phase(const Params& p, const Bufs& B, int l) {
;     const int wid = ltid() >> 6, lane = ltid() & 63;
;     const float* wconv = p.w_conv + (size_t)l * 3 * 1024; const float* bg = p.b_gates + l * 16;
;     const float* gq = p.g_q_norm + l * 512; const float* gkv = p.g_kv_norm + l * 256;
;     for (int s = lbid() * 8 + wid; s < S_; s += gridDim.x * 8) {
;         const bf16_t* pr = B.PROJ + (size_t)s * NPROJP;
;         const u32x4 z4 = (u32x4){0u, 0u, 0u, 0u};
;         u32x4 cm[2], cc[2], cp[2];
; #pragma unroll
;         for (int hf = 0; hf < 2; ++hf) { const int c0 = lane * 16 + hf * 8;
;             cm[hf] = s > 0 ? *(const u32x4*)(pr - NPROJP + c0) : z4; cc[hf] = *(const u32x4*)(pr + c0); cp[hf] = s < S_ - 1 ? *(const u32x4*)(pr + NPROJP + c0) : z4; }
;         const int tensor = lane >> 5, head = (lane & 31) >> 3, j0 = (lane & 7) * 4, base = PC_RQ + tensor * 256 + head * 64;
;         const u32x2 w1 = *(const u32x2*)(pr + base + j0), w2 = *(const u32x2*)(pr + base + 32 + j0);
;         const f32x4 rc4 = *(const f32x4*)(B.RC + (size_t)s * 32 + j0), rs4 = *(const f32x4*)(B.RS + (size_t)s * 32 + j0);
;         const u32x4 cqv = *(const u32x4*)(pr + PC_CQ + lane * 8); const u32x2 ckvv = *(const u32x2*)(pr + PC_CKV + lane * 4);
;         const int l32 = lane & 31, l16 = lane & 15;
;         const bf16_t kr1 = pr[PC_KR + l32], kr2 = pr[PC_KR + 32 + l32]; const float krc = B.RC[(size_t)s * 32 + l32], krs = B.RS[(size_t)s * 32 + l32];
;         const bf16_t gt = pr[PC_GATE + l16]; const float bgl = bg[l16];
; #pragma unroll
.LBB0_466:
	s_andn2_b64 vcc, exec, s[0:1]
	s_cbranch_vccnz .LBB0_536
	v_readlane_b32 s0, v254, 41
	s_cmp_gt_i32 s0, 0
	s_mov_b64 s[0:1], -1
	s_cbranch_scc0 .LBB0_502
	v_mov_b32_e32 v0, v192
	v_readlane_b32 s0, v252, 0
	s_waitcnt lgkmcnt(0)
	v_ashrrev_i32_e32 v1, 6, v0
	v_mov_b32_e32 v0, v192
	s_nop 0
	v_lshl_add_u32 v56, s0, 3, v1
	s_movk_i32 s0, 0x2000
	v_cmp_gt_i32_e32 vcc, s0, v56
	s_and_saveexec_b64 s[16:17], vcc
	s_cbranch_execz .LBB0_501
	v_readlane_b32 s36, v253, 2
	v_readlane_b32 s40, v253, 6
	v_readlane_b32 s41, v253, 7
	v_readlane_b32 s6, v254, 10
	v_readlane_b32 s42, v253, 8
	v_readlane_b32 s43, v253, 9
	v_readlane_b32 s44, v253, 10
	v_readlane_b32 s45, v253, 11
	v_readlane_b32 s46, v253, 12
	v_readlane_b32 s47, v253, 13
	v_readlane_b32 s48, v253, 14
	v_readlane_b32 s49, v253, 15
	v_readlane_b32 s50, v253, 16
	v_readlane_b32 s51, v253, 17
	s_mov_b64 s[20:21], s[40:41]
	s_mul_i32 s0, s6, 0x3000
	s_mov_b64 s[26:27], s[46:47]
	s_mul_hi_i32 s1, s6, 0x3000
	s_add_u32 s0, s26, s0
	v_readlane_b32 s37, v253, 3
	v_readlane_b32 s38, v253, 4
	v_readlane_b32 s39, v253, 5
	s_addc_u32 s1, s27, s1
	s_lshl_b32 s4, s6, 8
	s_mov_b64 s[22:23], s[42:43]
	s_mov_b64 s[24:25], s[44:45]
	s_mov_b64 s[28:29], s[48:49]
	s_mov_b64 s[30:31], s[50:51]
	s_ashr_i32 s5, s4, 31
	v_readlane_b32 s36, v253, 48
	s_lshl_b64 s[4:5], s[4:5], 2
	v_readlane_b32 s40, v253, 52
	v_readlane_b32 s41, v253, 53
	s_add_u32 s18, s40, s4
	s_addc_u32 s19, s41, s5
	s_lshl_b32 s4, s6, 9
	s_ashr_i32 s5, s4, 31
	s_lshl_b64 s[4:5], s[4:5], 2
	v_readlane_b32 s37, v253, 49
	s_add_u32 s20, s36, s4
	s_addc_u32 s21, s37, s5
	s_lshl_b32 s4, s6, 4
	s_ashr_i32 s5, s4, 31
	s_lshl_b64 s[4:5], s[4:5], 2
	s_add_u32 s4, s24, s4
	v_lshlrev_b32_e32 v1, 2, v0
	v_and_b32_e32 v8, 15, v0
	s_addc_u32 s5, s25, s5
	v_and_b32_e32 v3, 63, v0
	v_and_b32_e32 v2, 28, v1
	v_lshlrev_b32_e32 v1, 3, v0
	v_lshlrev_b32_e32 v10, 2, v8
	v_mov_b32_e32 v11, v195
	v_and_b32_e32 v60, 31, v0
	v_and_b32_e32 v9, 0xc0, v1
	v_lshl_add_u64 v[62:63], s[4:5], 0, v[10:11]
	v_cmp_gt_u32_e64 s[4:5], 32, v3
	v_mov_b32_e32 v1, 0x3e000000
	v_and_b32_e32 v0, 4, v0
	v_cndmask_b32_e64 v61, v1, 1.0, s[4:5]
	v_cmp_ne_u32_e64 s[8:9], 0, v0
	v_lshlrev_b32_e32 v0, 6, v3
	v_mov_b32_e32 v1, v195
	v_lshl_add_u64 v[68:69], s[0:1], 0, v[0:1]
	s_mov_b64 s[0:1], 0x1000
	v_lshlrev_b32_e32 v194, 3, v3
	v_lshl_add_u64 v[78:79], v[68:69], 0, s[0:1]
	s_mov_b64 s[0:1], 0x2000
	v_and_b32_e32 v5, 0x100, v194
	v_lshlrev_b32_e32 v10, 2, v2
	v_lshl_add_u64 v[80:81], v[68:69], 0, s[0:1]
	v_readlane_b32 s0, v254, 17
	v_lshl_add_u64 v[74:75], s[2:3], 0, v[10:11]
	v_lshl_add_u64 v[76:77], s[10:11], 0, v[10:11]
	v_lshlrev_b32_e32 v10, 1, v5
	v_readlane_b32 s1, v254, 18
	v_lshlrev_b32_e32 v6, 2, v3
	v_mov_b32_e32 v7, v195
	v_lshl_add_u64 v[10:11], s[0:1], 0, v[10:11]
	v_readlane_b32 s0, v254, 31
	v_readlane_b32 s1, v254, 32
	v_lshlrev_b32_e32 v12, 1, v9
	v_mov_b32_e32 v13, v195
	v_lshl_add_u64 v[88:89], s[0:1], 0, v[6:7]
	s_mov_b64 s[0:1], 0x1020
	v_lshl_add_u64 v[90:91], v[68:69], 0, s[0:1]
	s_mov_b64 s[0:1], 0x2020
	v_lshl_add_u64 v[92:93], v[68:69], 0, s[0:1]
	v_readlane_b32 s0, v254, 15
	v_lshlrev_b32_e32 v58, 4, v3
	v_or_b32_e32 v4, v5, v9
	v_mov_b32_e32 v59, v195
	v_lshlrev_b32_e32 v0, 5, v3
	v_lshl_add_u64 v[10:11], v[10:11], 0, v[12:13]
	v_lshlrev_b32_e32 v12, 1, v2
	v_readlane_b32 s1, v254, 16
	v_lshlrev_b32_e32 v64, 1, v3
	v_mov_b32_e32 v65, v195
	v_cmp_gt_u32_e64 s[6:7], 16, v3
	v_or_b32_e32 v66, 8, v58
	v_lshl_add_u64 v[70:71], s[20:21], 0, v[0:1]
	v_lshl_add_u64 v[72:73], s[18:19], 0, v[58:59]
	v_lshl_add_u64 v[82:83], v[10:11], 0, v[12:13]
	v_lshl_add_u64 v[84:85], s[12:13], 0, v[58:59]
	v_lshl_add_u64 v[86:87], s[14:15], 0, v[194:195]
	v_lshl_add_u64 v[94:95], s[0:1], 0, v[0:1]
	s_mov_b64 s[12:13], 0
	v_lshlrev_b32_e32 v96, 1, v4
	v_lshlrev_b32_e32 v98, 1, v2
	v_lshlrev_b32_e32 v100, 1, v194
	v_lshlrev_b32_e32 v102, 1, v6
	v_lshlrev_b32_e32 v104, 1, v8
	v_readlane_b32 s38, v253, 50
	v_readlane_b32 s39, v253, 51
	v_readlane_b32 s42, v253, 54
	v_readlane_b32 s43, v253, 55
	v_readlane_b32 s44, v253, 56
	v_readlane_b32 s45, v253, 57
	v_readlane_b32 s46, v253, 58
	v_readlane_b32 s47, v253, 59
	v_readlane_b32 s48, v253, 60
	v_readlane_b32 s49, v253, 61
	v_readlane_b32 s50, v253, 62
	v_readlane_b32 s51, v253, 63
	global_load_dwordx4 v[128:131], v[68:69], off offset:16
	global_load_dwordx4 v[132:135], v[68:69], off
	global_load_dwordx4 v[136:139], v[78:79], off offset:16
	global_load_dwordx4 v[140:143], v[78:79], off
	global_load_dwordx4 v[144:147], v[80:81], off offset:16
	global_load_dwordx4 v[148:151], v[80:81], off
	global_load_dwordx4 v[152:155], v[68:69], off offset:48
	global_load_dwordx4 v[156:159], v[68:69], off offset:32
	global_load_dwordx4 v[160:163], v[90:91], off offset:16
	global_load_dwordx4 v[164:167], v[90:91], off
	global_load_dwordx4 v[168:171], v[92:93], off offset:16
	global_load_dwordx4 v[172:175], v[92:93], off
	global_load_dwordx4 v[176:179], v[70:71], off offset:16
	global_load_dwordx4 v[180:183], v[70:71], off
	global_load_dwordx4 v[184:187], v[72:73], off
	s_branch .LBB0_488

; __device__ __forceinline__ int lbid() { int t = blockIdx.x; asm volatile("" : "+s"(t)); return t; }
; __device__ __forceinline__ void unpack8(u32x4 w, float* f) { f[0] = bflo(w.x); f[1] = bfhi(w.x); f[2] = bflo(w.y); f[3] = bfhi(w.y); f[4] = bflo(w.z); f[5] = bfhi(w.z); f[6] = bflo(w.w); f[7] = bfhi(w.w); }
; __device__ __forceinline__ u32x4 pack8(const float* f) { u32x4 w; w.x = cvt_pk_bf16(f[0], f[1]); w.y = cvt_pk_bf16(f[2], f[3]); w.z = cvt_pk_bf16(f[4], f[5]); w.w = cvt_pk_bf16(f[6], f[7]); return w; }
; __device__ __forceinline__ void prep_phase(const Params& p, const Bufs& B, int l) {
;     ...
;     for (int s = lbid() * 8 + wid; s < S_; s += gridDim.x * 8) {
;         const bf16_t* pr = B.PROJ + (size_t)s * NPROJP;
;         const u32x4 z4 = (u32x4){0u, 0u, 0u, 0u};
;         u32x4 cm[2], cc[2], cp[2];
; #pragma unroll
;         for (int hf = 0; hf < 2; ++hf) { const int c0 = lane * 16 + hf * 8;
;             cm[hf] = s > 0 ? *(const u32x4*)(pr - NPROJP + c0) : z4; cc[hf] = *(const u32x4*)(pr + c0); cp[hf] = s < S_ - 1 ? *(const u32x4*)(pr + NPROJP + c0) : z4; }
;         const int tensor = lane >> 5, head = (lane & 31) >> 3, j0 = (lane & 7) * 4, base = PC_RQ + tensor * 256 + head * 64;
;         const u32x2 w1 = *(const u32x2*)(pr + base + j0), w2 = *(const u32x2*)(pr + base + 32 + j0);
;         const f32x4 rc4 = *(const f32x4*)(B.RC + (size_t)s * 32 + j0), rs4 = *(const f32x4*)(B.RS + (size_t)s * 32 + j0);
;         const u32x4 cqv = *(const u32x4*)(pr + PC_CQ + lane * 8); const u32x2 ckvv = *(const u32x2*)(pr + PC_CKV + lane * 4);
;         const int l32 = lane & 31, l16 = lane & 15;
;         const bf16_t kr1 = pr[PC_KR + l32], kr2 = pr[PC_KR + 32 + l32]; const float krc = B.RC[(size_t)s * 32 + l32], krs = B.RS[(size_t)s * 32 + l32];
;         const bf16_t gt = pr[PC_GATE + l16]; const float bgl = bg[l16];
; #pragma unroll
;         for (int hf = 0; hf < 2; ++hf) { const int c0 = lane * 16 + hf * 8; float xm[8], x0[8], xp[8], r[8];
;             unpack8(cm[hf], xm); unpack8(cc[hf], x0); unpack8(cp[hf], xp);
; #pragma unroll
;             for (int i = 0; i < 8; ++i) { const float v = xm[i] * wconv[c0 + i] + x0[i] * wconv[1024 + c0 + i] + xp[i] * wconv[2048 + c0 + i]; r[i] = v * __builtin_amdgcn_rcpf(1.f + __expf(-v)); }
;             *(u32x4*)(B.QKML + (size_t)s * 1024 + c0) = pack8(r); }
.LBB0_496:
	s_or_b64 exec, exec, s[14:15]
	v_mov_b32_e32 v97, v195
	v_lshl_add_u64 v[0:1], v[36:37], 0, v[96:97]
	v_mov_b32_e32 v99, v195
	v_lshl_add_u64 v[0:1], v[0:1], 0, v[98:99]
	v_ashrrev_i32_e32 v57, 31, v56
	v_add_co_u32_e32 v0, vcc, 0x1000, v0
	v_lshlrev_b64 v[38:39], 7, v[56:57]
	s_nop 0
	v_addc_co_u32_e32 v1, vcc, 0, v1, vcc
	flat_load_dwordx2 v[108:109], v[0:1] offset:32
	flat_load_dwordx2 v[110:111], v[0:1] offset:96
	v_lshl_add_u64 v[0:1], v[74:75], 0, v[38:39]
	flat_load_dwordx4 v[4:7], v[0:1]
	v_lshl_add_u64 v[0:1], v[76:77], 0, v[38:39]
	v_mov_b32_e32 v101, v195
	flat_load_dwordx4 v[8:11], v[0:1]
	v_lshl_add_u64 v[0:1], v[36:37], 0, v[100:101]
	s_movk_i32 s1, 0x1000
	v_add_co_u32_e32 v0, vcc, s1, v0
	v_mov_b32_e32 v103, v195
	s_nop 0
	v_addc_co_u32_e32 v1, vcc, 0, v1, vcc
	v_lshl_add_u64 v[40:41], v[36:37], 0, v[102:103]
	s_movk_i32 s0, 0x2000
	v_add_co_u32_e32 v40, vcc, s0, v40
	v_lshlrev_b32_e32 v194, 1, v60
	s_nop 0
	v_addc_co_u32_e32 v41, vcc, 0, v41, vcc
	flat_load_dwordx4 v[0:3], v[0:1] offset:3104
	v_mov_b32_e32 v105, v195
	flat_load_dwordx2 v[106:107], v[40:41] offset:32
	v_lshl_add_u64 v[40:41], v[36:37], 0, v[194:195]
	v_add_co_u32_e32 v40, vcc, s0, v40
	v_lshl_add_u64 v[36:37], v[36:37], 0, v[104:105]
	s_nop 0
	v_addc_co_u32_e32 v41, vcc, 0, v41, vcc
	v_lshl_or_b32 v38, v60, 2, v38
	v_add_co_u32_e32 v36, vcc, s1, v36
	flat_load_ushort v97, v[40:41] offset:544
	flat_load_ushort v99, v[40:41] offset:608
	v_lshl_add_u64 v[40:41], s[2:3], 0, v[38:39]
	v_lshl_add_u64 v[38:39], s[10:11], 0, v[38:39]
	v_addc_co_u32_e32 v37, vcc, 0, v37, vcc
	flat_load_dword v101, v[40:41]
	flat_load_dword v103, v[38:39]
	flat_load_ushort v59, v[36:37]
	global_load_dword v67, v[62:63], off
	s_waitcnt vmcnt(0) lgkmcnt(0)
	v_lshlrev_b32_e32 v119, 16, v32
	v_and_b32_e32 v124, 0xffff0000, v32
	v_lshlrev_b32_e32 v118, 16, v33
	v_and_b32_e32 v117, 0xffff0000, v33
	v_lshlrev_b32_e32 v116, 16, v34
	v_and_b32_e32 v115, 0xffff0000, v34
	v_lshlrev_b32_e32 v114, 16, v35
	v_and_b32_e32 v105, 0xffff0000, v35
	v_mov_b64_e32 v[32:33], v[128:129]
	v_mov_b64_e32 v[34:35], v[130:131]
	v_mov_b64_e32 v[48:49], v[132:133]
	v_mov_b64_e32 v[50:51], v[134:135]
	v_mov_b64_e32 v[36:37], v[136:137]
	v_mov_b64_e32 v[38:39], v[138:139]
	v_mov_b64_e32 v[44:45], v[140:141]
	v_mov_b64_e32 v[46:47], v[142:143]
	v_mov_b64_e32 v[40:41], v[144:145]
	v_mov_b64_e32 v[42:43], v[146:147]
	v_mov_b64_e32 v[52:53], v[148:149]
	v_mov_b64_e32 v[54:55], v[150:151]
	v_lshlrev_b32_e32 v121, 16, v20
	v_lshlrev_b32_e32 v120, 16, v24
	v_lshlrev_b64 v[112:113], 11, v[56:57]
	s_waitcnt vmcnt(4)
	v_mov_b32_e32 v122, v48
	s_waitcnt vmcnt(0)
	v_mov_b32_e32 v123, v52
	v_pk_mul_f32 v[120:121], v[122:123], v[120:121]
	v_mov_b32_e32 v52, v49
	v_fma_f32 v44, v44, v119, v120
	v_add_f32_e32 v44, v44, v121
	v_mul_f32_e32 v48, 0xbfb8aa3b, v44
	v_exp_f32_e32 v48, v48
	v_and_b32_e32 v121, 0xffff0000, v20
	v_and_b32_e32 v120, 0xffff0000, v24
	v_add_f32_e32 v48, 1.0, v48
	v_rcp_f32_e32 v48, v48
	s_nop 0
	v_mul_f32_e32 v119, v44, v48
	v_pk_mul_f32 v[48:49], v[52:53], v[120:121]
	v_lshlrev_b32_e32 v44, 16, v25
	v_fma_f32 v20, v45, v124, v48
	v_add_f32_e32 v20, v20, v49
	v_mul_f32_e32 v24, 0xbfb8aa3b, v20
	v_exp_f32_e32 v24, v24
	v_lshlrev_b32_e32 v45, 16, v21
	v_mov_b32_e32 v48, v50
	v_mov_b32_e32 v49, v54
	v_add_f32_e32 v24, 1.0, v24
	v_rcp_f32_e32 v24, v24
	v_pk_mul_f32 v[44:45], v[48:49], v[44:45]
	v_and_b32_e32 v21, 0xffff0000, v21
	v_mov_b32_e32 v54, v51
	v_mul_f32_e32 v52, v20, v24
	v_fma_f32 v20, v46, v118, v44
	v_add_f32_e32 v20, v20, v45
	v_mul_f32_e32 v24, 0xbfb8aa3b, v20
	v_exp_f32_e32 v24, v24
	v_lshlrev_b32_e32 v50, 16, v28
	v_and_b32_e32 v51, 0xffff0000, v28
	v_and_b32_e32 v53, 0xffff0000, v29
	v_add_f32_e32 v24, 1.0, v24
	v_rcp_f32_e32 v24, v24
	v_lshlrev_b32_e32 v46, 16, v16
	v_mul_f32_e32 v44, v20, v24
	v_and_b32_e32 v20, 0xffff0000, v25
	v_pk_mul_f32 v[20:21], v[54:55], v[20:21]
	v_mov_b32_e32 v24, v32
	v_fma_f32 v20, v47, v117, v20
	v_add_f32_e32 v20, v20, v21
	v_mul_f32_e32 v21, 0xbfb8aa3b, v20
	v_exp_f32_e32 v21, v21
	v_mov_b32_e32 v25, v40
	v_mov_b32_e32 v40, v33
	v_lshlrev_b32_e32 v54, 16, v30
	v_add_f32_e32 v21, 1.0, v21
	v_rcp_f32_e32 v21, v21
	v_and_b32_e32 v55, 0xffff0000, v30
	v_lshlrev_b32_e32 v47, 16, v12
	v_mul_f32_e32 v45, v20, v21
	v_lshlrev_b32_e32 v21, 16, v22
	v_lshlrev_b32_e32 v20, 16, v26
	v_pk_mul_f32 v[20:21], v[24:25], v[20:21]
	v_mov_b32_e32 v24, v34
	v_fma_f32 v20, v36, v116, v20
	v_add_f32_e32 v20, v20, v21
	v_mul_f32_e32 v21, 0xbfb8aa3b, v20
	v_exp_f32_e32 v21, v21
	v_mov_b32_e32 v25, v42
	v_mov_b32_e32 v42, v35
	v_add_f32_e32 v21, 1.0, v21
	v_rcp_f32_e32 v21, v21
	s_nop 0
	v_mul_f32_e32 v32, v20, v21
	v_and_b32_e32 v21, 0xffff0000, v22
	v_and_b32_e32 v20, 0xffff0000, v26
	v_pk_mul_f32 v[20:21], v[40:41], v[20:21]
	s_nop 0
	v_fma_f32 v20, v37, v115, v20
	v_add_f32_e32 v20, v20, v21
	v_mul_f32_e32 v21, 0xbfb8aa3b, v20
	v_exp_f32_e32 v21, v21
	s_nop 0
	v_add_f32_e32 v21, 1.0, v21
	v_rcp_f32_e32 v21, v21
	s_nop 0
	v_mul_f32_e32 v22, v20, v21
	v_lshlrev_b32_e32 v20, 16, v27
	v_lshlrev_b32_e32 v21, 16, v23
	v_pk_mul_f32 v[20:21], v[24:25], v[20:21]
	s_nop 0
	v_fma_f32 v20, v38, v114, v20
	v_add_f32_e32 v20, v20, v21
	v_mul_f32_e32 v21, 0xbfb8aa3b, v20
	v_exp_f32_e32 v21, v21
	s_nop 0
	v_add_f32_e32 v21, 1.0, v21
	v_rcp_f32_e32 v21, v21
	s_nop 0
	v_mul_f32_e32 v24, v20, v21
	v_and_b32_e32 v21, 0xffff0000, v23
	v_and_b32_e32 v20, 0xffff0000, v27
	v_pk_mul_f32 v[20:21], v[42:43], v[20:21]
	s_nop 0
	v_fma_f32 v20, v39, v105, v20
	v_add_f32_e32 v20, v20, v21
	v_mul_f32_e32 v21, 0xbfb8aa3b, v20
	v_exp_f32_e32 v21, v21
	v_lshlrev_b32_e32 v105, 16, v31
	v_add_f32_e32 v21, 1.0, v21
	v_rcp_f32_e32 v21, v21
	s_nop 0
	v_mul_f32_e32 v23, v20, v21
	v_cvt_pk_bf16_f32 v20, v119, v52
	v_cvt_pk_bf16_f32 v21, v44, v45
	v_cvt_pk_bf16_f32 v22, v32, v22
	v_lshl_add_u64 v[32:33], v[94:95], 0, v[112:113]
	v_cvt_pk_bf16_f32 v23, v24, v23
	flat_store_dwordx4 v[32:33], v[20:23]
	v_lshlrev_b32_e32 v52, 16, v29
	v_and_b32_e32 v112, 0xffff0000, v31
	s_nop 1
	v_mov_b64_e32 v[20:21], v[152:153]
	v_mov_b64_e32 v[22:23], v[154:155]
	v_mov_b64_e32 v[34:35], v[156:157]
	v_mov_b64_e32 v[36:37], v[158:159]
	v_mov_b64_e32 v[24:25], v[160:161]
	v_mov_b64_e32 v[26:27], v[162:163]
	v_mov_b64_e32 v[38:39], v[164:165]
	v_mov_b64_e32 v[40:41], v[166:167]
	v_mov_b64_e32 v[28:29], v[168:169]
	v_mov_b64_e32 v[30:31], v[170:171]
	v_mov_b64_e32 v[42:43], v[172:173]
	v_mov_b64_e32 v[44:45], v[174:175]
	s_waitcnt vmcnt(0)
; __device__ __forceinline__ unsigned cvt_pk_bf16(float lo, float hi) { unsigned r; asm volatile("v_cvt_pk_bf16_f32 %0, %1, %2" : "=v"(r) : "v"(lo), "v"(hi)); return r; }
; __device__ __forceinline__ float bflo(unsigned w) { return __uint_as_float(w << 16); }
; __device__ __forceinline__ float bfhi(unsigned w) { return __uint_as_float(w & 0xffff0000u); }
; __device__ __forceinline__ void unpack8(u32x4 w, float* f) { f[0] = bflo(w.x); f[1] = bfhi(w.x); f[2] = bflo(w.y); f[3] = bfhi(w.y); f[4] = bflo(w.z); f[5] = bfhi(w.z); f[6] = bflo(w.w); f[7] = bfhi(w.w); }
; __device__ __forceinline__ void prep_phase(const Params& p, const Bufs& B, int l) {
;     ...
;         for (int hf = 0; hf < 2; ++hf) { const int c0 = lane * 16 + hf * 8; float xm[8], x0[8], xp[8], r[8];
;             unpack8(cm[hf], xm); unpack8(cc[hf], x0); unpack8(cp[hf], xp);
; #pragma unroll
;             for (int i = 0; i < 8; ++i) { const float v = xm[i] * wconv[c0 + i] + x0[i] * wconv[1024 + c0 + i] + xp[i] * wconv[2048 + c0 + i]; r[i] = v * __builtin_amdgcn_rcpf(1.f + __expf(-v)); }
;             *(u32x4*)(B.QKML + (size_t)s * 1024 + c0) = pack8(r); }
;         { const float x1[4] = {bflo(w1.x), bfhi(w1.x), bflo(w1.y), bfhi(w1.y)}, x2[4] = {bflo(w2.x), bfhi(w2.x), bflo(w2.y), bfhi(w2.y)};
;             const float sc = tensor ? 0.125f : 1.f; float o1[4], o2[4];
; #pragma unroll
;             for (int i = 0; i < 4; ++i) { o1[i] = (x1[i] * rc4[i] - x2[i] * rs4[i]) * sc; o2[i] = (x2[i] * rc4[i] + x1[i] * rs4[i]) * sc; }
;             u32x2 a, b2; a.x = cvt_pk_bf16(o1[0], o1[1]); a.y = cvt_pk_bf16(o1[2], o1[3]); b2.x = cvt_pk_bf16(o2[0], o2[1]); b2.y = cvt_pk_bf16(o2[2], o2[3]);
;             bf16_t* d = B.RQK + (size_t)s * 512 + tensor * 256 + head * 64 + j0; *(u32x2*)d = a; *(u32x2*)(d + 32) = b2; }
;         { float f[8]; unpack8(cqv, f); float g4[4] = {bflo(ckvv.x), bfhi(ckvv.x), bflo(ckvv.y), bfhi(ckvv.y)};
;             float ssq = 0.f, ssk = g4[0] * g4[0] + g4[1] * g4[1] + g4[2] * g4[2] + g4[3] * g4[3];
; #pragma unroll
;             for (int i = 0; i < 8; ++i) ssq += f[i] * f[i];
; #pragma unroll
;             for (int o = 32; o > 0; o >>= 1) { ssq += __shfl_xor(ssq, o); ssk += __shfl_xor(ssk, o); }
;             const float rstd = rsqrtf(ssq * (1.f / 512.f) + EPS_), rstk = rsqrtf(ssk * (1.f / 256.f) + EPS_);
	v_mov_b32_e32 v48, v34
	v_mov_b32_e32 v49, v42
	v_pk_mul_f32 v[46:47], v[48:49], v[46:47]
	v_mov_b32_e32 v42, v35
	v_fma_f32 v34, v38, v50, v46
	v_add_f32_e32 v34, v34, v47
	v_mul_f32_e32 v38, 0xbfb8aa3b, v34
	v_exp_f32_e32 v38, v38
	v_and_b32_e32 v47, 0xffff0000, v12
	v_and_b32_e32 v46, 0xffff0000, v16
	v_add_f32_e32 v38, 1.0, v38
	v_rcp_f32_e32 v38, v38
	s_nop 0
	v_mul_f32_e32 v48, v34, v38
	v_pk_mul_f32 v[34:35], v[42:43], v[46:47]
	v_mov_b32_e32 v38, v36
	v_fma_f32 v12, v39, v51, v34
	v_add_f32_e32 v12, v12, v35
	v_mul_f32_e32 v16, 0xbfb8aa3b, v12
	v_exp_f32_e32 v16, v16
	v_lshlrev_b32_e32 v34, 16, v17
	v_lshlrev_b32_e32 v35, 16, v13
	v_mov_b32_e32 v39, v44
	v_add_f32_e32 v16, 1.0, v16
	v_rcp_f32_e32 v16, v16
	v_pk_mul_f32 v[34:35], v[38:39], v[34:35]
	v_and_b32_e32 v13, 0xffff0000, v13
	v_mov_b32_e32 v44, v37
	v_mul_f32_e32 v42, v12, v16
	v_fma_f32 v12, v40, v52, v34
	v_add_f32_e32 v12, v12, v35
	v_mul_f32_e32 v16, 0xbfb8aa3b, v12
	v_exp_f32_e32 v16, v16
	s_nop 0
	v_add_f32_e32 v16, 1.0, v16
	v_rcp_f32_e32 v16, v16
	s_nop 0
	v_mul_f32_e32 v34, v12, v16
	v_and_b32_e32 v12, 0xffff0000, v17
	v_pk_mul_f32 v[12:13], v[44:45], v[12:13]
	v_mov_b32_e32 v16, v20
	v_fma_f32 v12, v41, v53, v12
	v_add_f32_e32 v12, v12, v13
	v_mul_f32_e32 v13, 0xbfb8aa3b, v12
	v_exp_f32_e32 v13, v13
	v_mov_b32_e32 v17, v28
	v_mov_b32_e32 v28, v21
	v_and_b32_e32 v21, s0, v3
	v_add_f32_e32 v13, 1.0, v13
	v_rcp_f32_e32 v13, v13
	s_mov_b32 s0, 0x3b800000
	s_mov_b32 s1, 0x3b000000
	v_mul_f32_e32 v35, v12, v13
	v_lshlrev_b32_e32 v13, 16, v14
	v_lshlrev_b32_e32 v12, 16, v18
	v_pk_mul_f32 v[12:13], v[16:17], v[12:13]
	v_mov_b32_e32 v16, v22
	v_fma_f32 v12, v24, v54, v12
	v_add_f32_e32 v12, v12, v13
	v_mul_f32_e32 v13, 0xbfb8aa3b, v12
	v_exp_f32_e32 v13, v13
	v_mov_b32_e32 v17, v30
	v_mov_b32_e32 v30, v23
	v_lshlrev_b32_e32 v23, 16, v2
	v_add_f32_e32 v13, 1.0, v13
	v_rcp_f32_e32 v13, v13
	v_and_b32_e32 v24, 0xffff0000, v3
	v_mul_f32_e32 v20, v12, v13
	v_and_b32_e32 v13, 0xffff0000, v14
	v_and_b32_e32 v12, 0xffff0000, v18
	v_pk_mul_f32 v[12:13], v[28:29], v[12:13]
	v_and_b32_e32 v18, 0xffff0000, v1
	v_fma_f32 v12, v25, v55, v12
	v_add_f32_e32 v12, v12, v13
	v_mul_f32_e32 v13, 0xbfb8aa3b, v12
	v_exp_f32_e32 v13, v13
	v_xor_b32_e32 v28, 4, v238
	v_lshlrev_b32_e32 v25, 16, v3
	v_add_f32_e32 v13, 1.0, v13
	v_rcp_f32_e32 v13, v13
	s_nop 0
	v_mul_f32_e32 v14, v12, v13
	v_lshlrev_b32_e32 v12, 16, v19
	v_lshlrev_b32_e32 v13, 16, v15
	v_pk_mul_f32 v[12:13], v[16:17], v[12:13]
	s_nop 0
	v_fma_f32 v12, v26, v105, v12
	v_add_f32_e32 v12, v12, v13
	v_mul_f32_e32 v13, 0xbfb8aa3b, v12
	v_exp_f32_e32 v13, v13
	s_nop 0
	v_add_f32_e32 v13, 1.0, v13
	v_rcp_f32_e32 v13, v13
	s_nop 0
	v_mul_f32_e32 v16, v12, v13
	v_and_b32_e32 v13, 0xffff0000, v15
	v_and_b32_e32 v12, 0xffff0000, v19
	v_pk_mul_f32 v[12:13], v[30:31], v[12:13]
	v_lshlrev_b32_e32 v19, 16, v1
	v_fma_f32 v12, v27, v112, v12
	v_add_f32_e32 v12, v12, v13
	v_mul_f32_e32 v13, 0xbfb8aa3b, v12
	v_exp_f32_e32 v13, v13
	s_nop 0
	v_add_f32_e32 v13, 1.0, v13
	v_rcp_f32_e32 v13, v13
	s_nop 0
	v_mul_f32_e32 v15, v12, v13
	v_cvt_pk_bf16_f32 v12, v48, v42
	v_cvt_pk_bf16_f32 v13, v34, v35
	v_cvt_pk_bf16_f32 v14, v20, v14
	v_cvt_pk_bf16_f32 v15, v16, v15
	flat_store_dwordx4 v[32:33], v[12:15] offset:16
	v_and_b32_e32 v20, 0xffff0000, v2
	v_mov_b32_e32 v22, v20
	v_lshlrev_b32_e32 v13, 16, v110
	v_lshlrev_b32_e32 v12, 16, v108
	v_mov_b32_e32 v14, v4
	v_mov_b32_e32 v15, v8
	v_pk_mul_f32 v[14:15], v[14:15], v[12:13]
	v_pk_mul_f32 v[26:27], v[20:21], v[20:21]
	v_sub_f32_e32 v14, v14, v15
	v_mul_f32_e32 v16, v61, v14
	v_mov_b32_e32 v14, v8
	v_mov_b32_e32 v15, v4
	v_pk_mul_f32 v[12:13], v[14:15], v[12:13]
	v_mov_b32_e32 v8, v5
	v_add_f32_e32 v4, v12, v13
	v_and_b32_e32 v13, 0xffff0000, v110
	v_and_b32_e32 v12, 0xffff0000, v108
	v_pk_mul_f32 v[14:15], v[8:9], v[12:13]
	v_mul_f32_e32 v17, v61, v4
	v_sub_f32_e32 v4, v14, v15
	v_mul_f32_e32 v14, v61, v4
	v_mov_b32_e32 v4, v9
	v_pk_mul_f32 v[4:5], v[4:5], v[12:13]
	v_mov_b32_e32 v8, v6
	v_add_f32_e32 v4, v4, v5
	v_mul_f32_e32 v12, v61, v4
	v_lshlrev_b32_e32 v5, 16, v111
	v_lshlrev_b32_e32 v4, 16, v109
	v_mov_b32_e32 v9, v10
	v_pk_mul_f32 v[8:9], v[8:9], v[4:5]
	v_xor_b32_e32 v21, 32, v238
	v_sub_f32_e32 v8, v8, v9
	v_mul_f32_e32 v13, v61, v8
	v_mov_b32_e32 v8, v10
	v_mov_b32_e32 v9, v6
	v_pk_mul_f32 v[4:5], v[8:9], v[4:5]
	v_mov_b32_e32 v10, v7
	v_add_f32_e32 v4, v4, v5
	v_mul_f32_e32 v15, v61, v4
	v_and_b32_e32 v5, 0xffff0000, v111
	v_and_b32_e32 v4, 0xffff0000, v109
	v_pk_mul_f32 v[8:9], v[10:11], v[4:5]
	v_xor_b32_e32 v27, 8, v238
	v_sub_f32_e32 v6, v8, v9
	v_mul_f32_e32 v8, v61, v6
	v_mov_b32_e32 v6, v11
	v_pk_mul_f32 v[4:5], v[6:7], v[4:5]
	v_mov_b32_e32 v29, v26
	v_add_f32_e32 v4, v4, v5
	v_mul_f32_e32 v7, v61, v4
	v_cvt_pk_bf16_f32 v4, v16, v14
	v_cvt_pk_bf16_f32 v5, v13, v8
	v_cvt_pk_bf16_f32 v6, v17, v12
	v_cvt_pk_bf16_f32 v7, v15, v7
	v_lshlrev_b64 v[14:15], 10, v[56:57]
	v_lshl_add_u64 v[10:11], v[82:83], 0, v[14:15]
	v_lshlrev_b32_e32 v16, 16, v0
	v_and_b32_e32 v17, 0xffff0000, v0
	flat_store_dwordx2 v[10:11], v[4:5]
	flat_store_dwordx2 v[10:11], v[6:7] offset:64
	v_pk_mul_f32 v[6:7], v[16:17], v[16:17]
	v_pk_mul_f32 v[0:1], v[18:19], v[18:19]
	v_add_f32_e32 v2, v6, v7
	v_add_f32_e32 v1, v1, v2
	v_add_f32_e32 v0, v0, v1
	v_pk_fma_f32 v[0:1], v[22:23], v[22:23], v[0:1] op_sel_hi:[1,1,0]
	v_xor_b32_e32 v22, 16, v238
	v_and_b32_e32 v0, 64, v238
	v_add_u32_e32 v0, 64, v0
	v_cmp_lt_i32_e32 vcc, v21, v0
	v_lshlrev_b32_e32 v12, 16, v106
	v_and_b32_e32 v13, 0xffff0000, v106
	v_cndmask_b32_e32 v21, v238, v21, vcc
	v_cmp_lt_i32_e32 vcc, v22, v0
	v_and_b32_e32 v10, 0xffff0000, v107
	v_lshlrev_b32_e32 v11, 16, v107
	v_cndmask_b32_e32 v22, v238, v22, vcc
	v_cmp_lt_i32_e32 vcc, v27, v0
	v_pk_mul_f32 v[6:7], v[12:13], v[12:13]
	v_pk_mul_f32 v[4:5], v[10:11], v[10:11]
	v_cndmask_b32_e32 v27, v238, v27, vcc
	v_cmp_lt_i32_e32 vcc, v28, v0
	v_pk_mul_f32 v[2:3], v[24:25], v[24:25]
	v_lshlrev_b32_e32 v21, 2, v21
	v_cndmask_b32_e32 v28, v238, v28, vcc
	v_lshlrev_b32_e32 v30, 2, v28
	v_xor_b32_e32 v28, 2, v238
	v_cmp_lt_i32_e32 vcc, v28, v0
	v_lshlrev_b32_e32 v22, 2, v22
	v_lshlrev_b32_e32 v27, 2, v27
	v_cndmask_b32_e32 v28, v238, v28, vcc
	v_lshlrev_b32_e32 v31, 2, v28
	v_xor_b32_e32 v28, 1, v238
	v_cmp_lt_i32_e32 vcc, v28, v0
	v_lshlrev_b64 v[8:9], 9, v[56:57]
	s_nop 0
	v_cndmask_b32_e32 v0, v238, v28, vcc
	v_lshlrev_b32_e32 v32, 2, v0
	v_mov_b32_e32 v28, v6
	v_mov_b32_e32 v0, v7
	v_pk_add_f32 v[0:1], v[28:29], v[0:1]
	v_mov_b32_e32 v6, v5
	v_mov_b32_e32 v7, v3
	v_pk_add_f32 v[0:1], v[6:7], v[0:1]
	v_mov_b32_e32 v5, v2
	v_pk_add_f32 v[0:1], v[4:5], v[0:1]
	ds_bpermute_b32 v3, v21, v1
	ds_bpermute_b32 v2, v21, v0
	s_waitcnt lgkmcnt(0)
; __device__ __forceinline__ unsigned cvt_pk_bf16(float lo, float hi) { unsigned r; asm volatile("v_cvt_pk_bf16_f32 %0, %1, %2" : "=v"(r) : "v"(lo), "v"(hi)); return r; }
; __device__ __forceinline__ float bf2f(bf16_t b) { return __uint_as_float(((unsigned)b) << 16); }
; __device__ __forceinline__ u32x4 pack8(const float* f) { u32x4 w; w.x = cvt_pk_bf16(f[0], f[1]); w.y = cvt_pk_bf16(f[2], f[3]); w.z = cvt_pk_bf16(f[4], f[5]); w.w = cvt_pk_bf16(f[6], f[7]); return w; }
; __device__ __forceinline__ void prep_phase(const Params& p, const Bufs& B, int l) {
;     ...
;             for (int o = 32; o > 0; o >>= 1) { ssq += __shfl_xor(ssq, o); ssk += __shfl_xor(ssk, o); }
;             const float rstd = rsqrtf(ssq * (1.f / 512.f) + EPS_), rstk = rsqrtf(ssk * (1.f / 256.f) + EPS_);
; #pragma unroll
;             for (int i = 0; i < 8; ++i) f[i] = f[i] * rstd * gq[lane * 8 + i];
;             *(u32x4*)(B.CQN + (size_t)s * 512 + lane * 8) = pack8(f);
; #pragma unroll
;             for (int i = 0; i < 4; ++i) g4[i] = g4[i] * rstk * gkv[lane * 4 + i];
;             u32x2 o; o.x = cvt_pk_bf16(g4[0], g4[1]); o.y = cvt_pk_bf16(g4[2], g4[3]); *(u32x2*)(B.CKVN + (size_t)s * 256 + lane * 4) = o; }
;         if (lane < 32) { const float x1 = bf2f(kr1), x2 = bf2f(kr2);
;             const unsigned short w = (unsigned short)(__builtin_amdgcn_cvt_pk_fp8_f32(x1 * krc - x2 * krs, x2 * krc + x1 * krs, 0, false) & 0xffff);
; #pragma unroll
;             for (int h = 0; h < 8; ++h) *(unsigned short*)((unsigned char*)B.K + ((size_t)h * S_ + s) * 192 + 128 + 2 * lane) = w; }
	v_pk_add_f32 v[0:1], v[0:1], v[2:3]
	ds_bpermute_b32 v3, v22, v1
	ds_bpermute_b32 v2, v22, v0
	s_waitcnt lgkmcnt(0)
	v_pk_add_f32 v[0:1], v[0:1], v[2:3]
	ds_bpermute_b32 v3, v27, v1
	ds_bpermute_b32 v2, v27, v0
	s_waitcnt lgkmcnt(0)
	v_pk_add_f32 v[0:1], v[0:1], v[2:3]
	ds_bpermute_b32 v3, v30, v1
	ds_bpermute_b32 v2, v30, v0
	s_waitcnt lgkmcnt(0)
	v_pk_add_f32 v[0:1], v[0:1], v[2:3]
	ds_bpermute_b32 v3, v31, v1
	ds_bpermute_b32 v2, v31, v0
	s_waitcnt lgkmcnt(0)
	v_pk_add_f32 v[0:1], v[0:1], v[2:3]
	ds_bpermute_b32 v3, v32, v1
	ds_bpermute_b32 v2, v32, v0
	s_waitcnt lgkmcnt(0)
	v_pk_add_f32 v[0:1], v[0:1], v[2:3]
	s_nop 0
	v_pk_fma_f32 v[0:1], v[0:1], s[0:1], v[242:243] op_sel_hi:[1,1,0]
	s_mov_b32 s0, 0x800000
	v_mul_f32_e32 v2, 0x4b800000, v1
	v_cmp_gt_f32_e32 vcc, s0, v0
	v_cmp_gt_f32_e64 s[0:1], s0, v1
	s_nop 1
	v_cndmask_b32_e64 v1, v1, v2, s[0:1]
	v_rsq_f32_e32 v1, v1
	s_nop 0
	v_mul_f32_e32 v2, 0x45800000, v1
	v_cndmask_b32_e64 v21, v1, v2, s[0:1]
	v_mul_f32_e32 v21, 0x3f553b94, v21
	v_mul_f32_e32 v1, 0x4b800000, v0
	v_cndmask_b32_e32 v0, v0, v1, vcc
	v_rsq_f32_e32 v22, v0
	v_mov_b64_e32 v[0:1], v[176:177]
	v_mov_b64_e32 v[2:3], v[178:179]
	v_mov_b64_e32 v[4:5], v[180:181]
	v_mov_b64_e32 v[6:7], v[182:183]
	v_mul_f32_e32 v16, v21, v16
	v_mul_f32_e32 v26, 0x45800000, v22
	s_waitcnt vmcnt(0)
	v_mul_f32_e32 v4, v4, v16
	v_mul_f32_e32 v16, v21, v17
	v_mul_f32_e32 v5, v5, v16
	v_mul_f32_e32 v16, v21, v19
	v_mul_f32_e32 v6, v6, v16
	v_mul_f32_e32 v16, v21, v18
	v_mul_f32_e32 v7, v7, v16
	v_mul_f32_e32 v16, v21, v23
	v_mul_f32_e32 v16, v0, v16
	v_mul_f32_e32 v0, v21, v20
	v_mul_f32_e32 v17, v1, v0
	v_mul_f32_e32 v0, v21, v25
	v_mul_f32_e32 v18, v2, v0
	v_mul_f32_e32 v0, v21, v24
	v_mul_f32_e32 v3, v3, v0
	v_cvt_pk_bf16_f32 v0, v4, v5
	v_lshl_add_u64 v[4:5], v[84:85], 0, v[14:15]
	v_cvt_pk_bf16_f32 v1, v6, v7
	v_cvt_pk_bf16_f32 v2, v16, v17
	v_cvt_pk_bf16_f32 v3, v18, v3
	flat_store_dwordx4 v[4:5], v[0:3]
	s_nop 1
	v_mov_b64_e32 v[0:1], v[184:185]
	v_mov_b64_e32 v[2:3], v[186:187]
	v_cndmask_b32_e32 v19, v22, v26, vcc
	v_mul_f32_e32 v4, v19, v12
	s_waitcnt vmcnt(0)
	v_mul_f32_e32 v0, v4, v0
	v_mul_f32_e32 v4, v19, v13
	v_mul_f32_e32 v1, v4, v1
	v_mul_f32_e32 v4, v19, v11
	v_mul_f32_e32 v2, v4, v2
	v_mul_f32_e32 v4, v19, v10
	v_mul_f32_e32 v3, v4, v3
	v_cvt_pk_bf16_f32 v0, v0, v1
	v_cvt_pk_bf16_f32 v1, v2, v3
	v_lshl_add_u64 v[2:3], v[86:87], 0, v[8:9]
	flat_store_dwordx2 v[2:3], v[0:1]
	s_and_saveexec_b64 s[0:1], s[4:5]
	s_cbranch_execz .LBB0_498
	v_lshlrev_b32_e32 v1, 16, v99
	v_lshlrev_b32_e32 v0, 16, v97
	v_mul_f32_e32 v2, v103, v1
	v_mul_f32_e32 v1, v101, v1
	v_readlane_b32 s14, v254, 27
	v_fma_f32 v2, v101, v0, -v2
	v_fmac_f32_e32 v1, v103, v0
	v_mov_b32_e32 v4, v195
	v_readlane_b32 s15, v254, 28
	v_cvt_pk_fp8_f32 v4, v2, v1
	s_nop 0
	v_mov_b64_e32 v[0:1], s[14:15]
	s_movk_i32 s14, 0xc0
	v_mad_i64_i32 v[0:1], s[14:15], v56, s14, v[0:1]
	v_lshl_add_u64 v[0:1], v[0:1], 0, v[64:65]
	v_add_co_u32_e32 v2, vcc, 0x180000, v0
	flat_store_short v[0:1], v4 offset:128
	s_nop 0
	v_addc_co_u32_e32 v3, vcc, 0, v1, vcc
	flat_store_short v[2:3], v4 offset:128
	v_add_co_u32_e32 v2, vcc, 0x300000, v0
	s_nop 1
	v_addc_co_u32_e32 v3, vcc, 0, v1, vcc
	flat_store_short v[2:3], v4 offset:128
	v_add_co_u32_e32 v2, vcc, 0x480000, v0
	s_nop 1
	v_addc_co_u32_e32 v3, vcc, 0, v1, vcc
	flat_store_short v[2:3], v4 offset:128
	v_add_co_u32_e32 v2, vcc, 0x600000, v0
	s_nop 1
	v_addc_co_u32_e32 v3, vcc, 0, v1, vcc
	flat_store_short v[2:3], v4 offset:128
	v_add_co_u32_e32 v2, vcc, 0x780000, v0
	s_nop 1
	v_addc_co_u32_e32 v3, vcc, 0, v1, vcc
	flat_store_short v[2:3], v4 offset:128
	v_add_co_u32_e32 v2, vcc, 0x900000, v0
	s_nop 1
	v_addc_co_u32_e32 v3, vcc, 0, v1, vcc
	v_add_co_u32_e32 v0, vcc, 0xa80000, v0
	flat_store_short v[2:3], v4 offset:128
	s_nop 0
	v_addc_co_u32_e32 v1, vcc, 0, v1, vcc
	flat_store_short v[0:1], v4 offset:128
